# in-proj K loop: first half-iteration peeled with SrcC=0 (no accumulator zeroing movs)
# speedup vs baseline: 1.0063x; 1.0063x over previous
.LBB0_156:
	s_cmp_gt_u32 s75, 1
	s_cselect_b32 s92, 1, 0
	s_ashr_i32 s15, s14, 31
	s_lshl_b64 s[18:19], s[14:15], 19
	s_add_u32 s18, s54, s18
	s_addc_u32 s19, s55, s19
	s_and_b64 s[20:21], s[16:17], exec
	s_cselect_b32 s15, s19, s27
	s_cselect_b32 s23, s18, s26
	s_ashr_i32 s13, s12, 31
	s_lshl_b64 s[20:21], s[12:13], 19
	s_add_u32 s20, s3, s20
	s_addc_u32 s21, s68, s21
	s_and_b64 s[30:31], s[16:17], exec
	s_cselect_b32 s13, s21, s29
	s_cselect_b32 s25, s20, s28
	s_add_u32 s26, s26, 0x40080
	s_addc_u32 s27, s27, 0
	s_add_u32 s36, s28, 0x100
	s_addc_u32 s37, s29, 0
	s_mov_b32 s38, -2
	v_add_u32_e32 v172, s81, v175
	ds_read_b128 v[164:167], v172
	ds_read_b128 v[168:171], v172 offset:1024
	ds_read_b128 v[182:185], v172 offset:2048
	ds_read_b128 v[186:189], v172 offset:3072
	v_add_u32_e32 v172, s82, v175
	ds_read_b128 v[190:193], v172
	ds_read_b128 v[194:197], v172 offset:1024
	ds_read_b128 v[200:203], v172 offset:2048
	ds_read_b128 v[204:207], v172 offset:3072
	s_add_u32 s28, s26, 0xfffc0080
	s_addc_u32 s29, s27, -1
	s_cmp_eq_u32 s38, 12
	s_cselect_b32 s31, s15, s29
	s_cselect_b32 s30, s23, s28
	s_cselect_b32 s29, s13, s37
	s_cselect_b32 s28, s25, s36
	v_lshl_add_u64 v[172:173], s[26:27], 0, v[158:159]
	s_add_i32 m0, s71, 0xc000
	ds_read_b128 v[208:211], v180
	ds_read_b128 v[212:215], v180 offset:1024
	ds_read_b128 v[216:219], v180 offset:2048
	ds_read_b128 v[220:223], v180 offset:3072
	ds_read_b128 v[224:227], v180 offset:4096
	ds_read_b128 v[228:231], v180 offset:5120
	ds_read_b128 v[232:235], v180 offset:6144
	ds_read_b128 v[236:239], v180 offset:7168
	global_load_lds_dwordx4 v[172:173], off
	v_lshl_add_u64 v[172:173], s[26:27], 0, v[160:161]
	s_add_i32 m0, s71, 0xe000
	s_nop 0
	global_load_lds_dwordx4 v[172:173], off
	s_cmp_eq_u32 s92, 0
	s_cbranch_scc1 .Lp1z_w8_0
	s_waitcnt vmcnt(24)
	s_branch .Lp1z_wd_0

.Lp1z_wd_0:
	s_waitcnt lgkmcnt(0)
	s_barrier
	s_setprio 1
	s_waitcnt lgkmcnt(0)
	v_mfma_f32_16x16x32_bf16 v[124:127], v[164:167], v[208:211], 0
	v_mfma_f32_16x16x32_bf16 v[120:123], v[182:185], v[208:211], 0
	v_mfma_f32_16x16x32_bf16 v[108:111], v[164:167], v[216:219], 0
	v_mfma_f32_16x16x32_bf16 v[104:107], v[182:185], v[216:219], 0
	v_mfma_f32_16x16x32_bf16 v[92:95], v[164:167], v[224:227], 0
	v_mfma_f32_16x16x32_bf16 v[88:91], v[182:185], v[224:227], 0
	v_mfma_f32_16x16x32_bf16 v[76:79], v[164:167], v[232:235], 0
	v_mfma_f32_16x16x32_bf16 v[72:75], v[182:185], v[232:235], 0
	v_mfma_f32_16x16x32_bf16 v[124:127], v[168:171], v[212:215], v[124:127]
	v_mfma_f32_16x16x32_bf16 v[120:123], v[186:189], v[212:215], v[120:123]
	v_mfma_f32_16x16x32_bf16 v[108:111], v[168:171], v[220:223], v[108:111]
	v_mfma_f32_16x16x32_bf16 v[104:107], v[186:189], v[220:223], v[104:107]
	v_mfma_f32_16x16x32_bf16 v[92:95], v[168:171], v[228:231], v[92:95]
	v_mfma_f32_16x16x32_bf16 v[88:91], v[186:189], v[228:231], v[88:91]
	v_mfma_f32_16x16x32_bf16 v[76:79], v[168:171], v[236:239], v[76:79]
	v_mfma_f32_16x16x32_bf16 v[72:75], v[186:189], v[236:239], v[72:75]
	s_setprio 0
	s_setprio 1
	v_mfma_f32_16x16x32_bf16 v[116:119], v[190:193], v[208:211], 0
	v_mfma_f32_16x16x32_bf16 v[112:115], v[200:203], v[208:211], 0
	v_mfma_f32_16x16x32_bf16 v[100:103], v[190:193], v[216:219], 0
	v_mfma_f32_16x16x32_bf16 v[96:99], v[200:203], v[216:219], 0
	v_mfma_f32_16x16x32_bf16 v[84:87], v[190:193], v[224:227], 0
	v_mfma_f32_16x16x32_bf16 v[80:83], v[200:203], v[224:227], 0
	v_mfma_f32_16x16x32_bf16 v[68:71], v[190:193], v[232:235], 0
	v_mfma_f32_16x16x32_bf16 v[64:67], v[200:203], v[232:235], 0
	v_mfma_f32_16x16x32_bf16 v[116:119], v[194:197], v[212:215], v[116:119]
	v_mfma_f32_16x16x32_bf16 v[112:115], v[204:207], v[212:215], v[112:115]
	v_mfma_f32_16x16x32_bf16 v[100:103], v[194:197], v[220:223], v[100:103]
	v_mfma_f32_16x16x32_bf16 v[96:99], v[204:207], v[220:223], v[96:99]
	v_mfma_f32_16x16x32_bf16 v[84:87], v[194:197], v[228:231], v[84:87]
	v_mfma_f32_16x16x32_bf16 v[80:83], v[204:207], v[228:231], v[80:83]
	v_mfma_f32_16x16x32_bf16 v[68:71], v[194:197], v[236:239], v[68:71]
	v_mfma_f32_16x16x32_bf16 v[64:67], v[204:207], v[236:239], v[64:67]
	s_setprio 0
	s_barrier
	s_add_i32 s39, s81, s70
	v_lshl_add_u64 v[172:173], s[28:29], 0, v[130:131]
	s_mov_b32 m0, s39
	ds_read_b128 v[208:211], v180 offset:16384
	ds_read_b128 v[212:215], v180 offset:17408
	ds_read_b128 v[216:219], v180 offset:18432
	ds_read_b128 v[220:223], v180 offset:19456
	ds_read_b128 v[224:227], v180 offset:20480
	ds_read_b128 v[228:231], v180 offset:21504
	ds_read_b128 v[232:235], v180 offset:22528
	ds_read_b128 v[236:239], v180 offset:23552
	global_load_lds_dwordx4 v[172:173], off
	s_add_i32 m0, s39, 0x2000
	s_add_u32 s40, s28, 0x40000
	v_lshl_add_u64 v[240:241], s[28:29], 0, v[134:135]
	s_addc_u32 s41, s29, 0
	s_add_i32 s39, s82, s70
	global_load_lds_dwordx4 v[240:241], off
	v_lshl_add_u64 v[242:243], s[40:41], 0, v[130:131]
	s_mov_b32 m0, s39
	v_lshl_add_u64 v[244:245], s[30:31], 0, v[132:133]
	global_load_lds_dwordx4 v[242:243], off
	v_lshl_add_u64 v[242:243], s[40:41], 0, v[134:135]
	s_add_i32 m0, s39, 0x2000
	s_nop 0
	global_load_lds_dwordx4 v[242:243], off
	v_lshl_add_u64 v[242:243], s[30:31], 0, v[128:129]
	s_mov_b32 m0, s71
	s_nop 0
	global_load_lds_dwordx4 v[242:243], off
	s_mov_b32 m0, s72
	s_nop 0
	global_load_lds_dwordx4 v[244:245], off
	s_cmp_eq_u32 s92, 0
	s_cbranch_scc1 .Lp1z_w8_1
	s_waitcnt vmcnt(24)
	s_branch .Lp1z_wd_1

.Lp1z_wd_1:
	s_mov_b32 s92, 0
	s_waitcnt lgkmcnt(0)
	s_barrier
	s_setprio 1
	s_waitcnt lgkmcnt(0)
	v_mfma_f32_16x16x32_bf16 v[60:63], v[164:167], v[208:211], 0
	v_mfma_f32_16x16x32_bf16 v[56:59], v[182:185], v[208:211], 0
	v_mfma_f32_16x16x32_bf16 v[44:47], v[164:167], v[216:219], 0
	v_mfma_f32_16x16x32_bf16 v[40:43], v[182:185], v[216:219], 0
	v_mfma_f32_16x16x32_bf16 v[28:31], v[164:167], v[224:227], 0
	v_mfma_f32_16x16x32_bf16 v[24:27], v[182:185], v[224:227], 0
	v_mfma_f32_16x16x32_bf16 v[12:15], v[164:167], v[232:235], 0
	v_mfma_f32_16x16x32_bf16 v[8:11], v[182:185], v[232:235], 0
	v_mfma_f32_16x16x32_bf16 v[60:63], v[168:171], v[212:215], v[60:63]
	v_mfma_f32_16x16x32_bf16 v[56:59], v[186:189], v[212:215], v[56:59]
	v_mfma_f32_16x16x32_bf16 v[44:47], v[168:171], v[220:223], v[44:47]
	v_mfma_f32_16x16x32_bf16 v[40:43], v[186:189], v[220:223], v[40:43]
	v_mfma_f32_16x16x32_bf16 v[28:31], v[168:171], v[228:231], v[28:31]
	v_mfma_f32_16x16x32_bf16 v[24:27], v[186:189], v[228:231], v[24:27]
	v_mfma_f32_16x16x32_bf16 v[12:15], v[168:171], v[236:239], v[12:15]
	v_mfma_f32_16x16x32_bf16 v[8:11], v[186:189], v[236:239], v[8:11]
	s_setprio 0
	s_setprio 1
	v_mfma_f32_16x16x32_bf16 v[52:55], v[190:193], v[208:211], 0
	v_mfma_f32_16x16x32_bf16 v[48:51], v[200:203], v[208:211], 0
	v_mfma_f32_16x16x32_bf16 v[36:39], v[190:193], v[216:219], 0
	v_mfma_f32_16x16x32_bf16 v[32:35], v[200:203], v[216:219], 0
	v_mfma_f32_16x16x32_bf16 v[20:23], v[190:193], v[224:227], 0
	v_mfma_f32_16x16x32_bf16 v[16:19], v[200:203], v[224:227], 0
	v_mfma_f32_16x16x32_bf16 v[4:7], v[190:193], v[232:235], 0
	v_mfma_f32_16x16x32_bf16 v[0:3], v[200:203], v[232:235], 0
	v_mfma_f32_16x16x32_bf16 v[52:55], v[194:197], v[212:215], v[52:55]
	v_mfma_f32_16x16x32_bf16 v[48:51], v[204:207], v[212:215], v[48:51]
	v_mfma_f32_16x16x32_bf16 v[36:39], v[194:197], v[220:223], v[36:39]
	v_mfma_f32_16x16x32_bf16 v[32:35], v[204:207], v[220:223], v[32:35]
	v_mfma_f32_16x16x32_bf16 v[20:23], v[194:197], v[228:231], v[20:23]
	v_mfma_f32_16x16x32_bf16 v[16:19], v[204:207], v[228:231], v[16:19]
	v_mfma_f32_16x16x32_bf16 v[4:7], v[194:197], v[236:239], v[4:7]
	v_mfma_f32_16x16x32_bf16 v[0:3], v[204:207], v[236:239], v[0:3]
	s_setprio 0
	s_barrier
	s_branch .Lp1_seg3
.LBB0_157:
	v_add_u32_e32 v172, s81, v175
	ds_read_b128 v[164:167], v172
	ds_read_b128 v[168:171], v172 offset:1024
	ds_read_b128 v[182:185], v172 offset:2048
	ds_read_b128 v[186:189], v172 offset:3072
	v_add_u32_e32 v172, s82, v175
	ds_read_b128 v[190:193], v172
	ds_read_b128 v[194:197], v172 offset:1024
	ds_read_b128 v[200:203], v172 offset:2048
	ds_read_b128 v[204:207], v172 offset:3072
	s_add_u32 s28, s26, 0xfffc0080
	s_addc_u32 s29, s27, -1
	s_cmp_eq_u32 s38, 12
	s_cselect_b32 s31, s15, s29
	s_cselect_b32 s30, s23, s28
	s_cselect_b32 s29, s13, s37
	s_cselect_b32 s28, s25, s36
	v_lshl_add_u64 v[172:173], s[26:27], 0, v[158:159]
	s_add_i32 m0, s71, 0xc000
	ds_read_b128 v[208:211], v180
	ds_read_b128 v[212:215], v180 offset:1024
	ds_read_b128 v[216:219], v180 offset:2048
	ds_read_b128 v[220:223], v180 offset:3072
	ds_read_b128 v[224:227], v180 offset:4096
	ds_read_b128 v[228:231], v180 offset:5120
	ds_read_b128 v[232:235], v180 offset:6144
	ds_read_b128 v[236:239], v180 offset:7168
	global_load_lds_dwordx4 v[172:173], off
	v_lshl_add_u64 v[172:173], s[26:27], 0, v[160:161]
	s_add_i32 m0, s71, 0xe000
	s_nop 0
	global_load_lds_dwordx4 v[172:173], off
	s_waitcnt vmcnt(8)
	s_waitcnt lgkmcnt(0)
	s_barrier
	s_setprio 1
	s_waitcnt lgkmcnt(0)
	v_mfma_f32_16x16x32_bf16 v[124:127], v[164:167], v[208:211], v[124:127]
	v_mfma_f32_16x16x32_bf16 v[120:123], v[182:185], v[208:211], v[120:123]
	v_mfma_f32_16x16x32_bf16 v[108:111], v[164:167], v[216:219], v[108:111]
	v_mfma_f32_16x16x32_bf16 v[104:107], v[182:185], v[216:219], v[104:107]
	v_mfma_f32_16x16x32_bf16 v[92:95], v[164:167], v[224:227], v[92:95]
	v_mfma_f32_16x16x32_bf16 v[88:91], v[182:185], v[224:227], v[88:91]
	v_mfma_f32_16x16x32_bf16 v[76:79], v[164:167], v[232:235], v[76:79]
	v_mfma_f32_16x16x32_bf16 v[72:75], v[182:185], v[232:235], v[72:75]
	v_mfma_f32_16x16x32_bf16 v[124:127], v[168:171], v[212:215], v[124:127]
	v_mfma_f32_16x16x32_bf16 v[120:123], v[186:189], v[212:215], v[120:123]
	v_mfma_f32_16x16x32_bf16 v[108:111], v[168:171], v[220:223], v[108:111]
	v_mfma_f32_16x16x32_bf16 v[104:107], v[186:189], v[220:223], v[104:107]
	v_mfma_f32_16x16x32_bf16 v[92:95], v[168:171], v[228:231], v[92:95]
	v_mfma_f32_16x16x32_bf16 v[88:91], v[186:189], v[228:231], v[88:91]
	v_mfma_f32_16x16x32_bf16 v[76:79], v[168:171], v[236:239], v[76:79]
	v_mfma_f32_16x16x32_bf16 v[72:75], v[186:189], v[236:239], v[72:75]
	s_setprio 0
	s_setprio 1
	v_mfma_f32_16x16x32_bf16 v[116:119], v[190:193], v[208:211], v[116:119]
	v_mfma_f32_16x16x32_bf16 v[112:115], v[200:203], v[208:211], v[112:115]
	v_mfma_f32_16x16x32_bf16 v[100:103], v[190:193], v[216:219], v[100:103]
	v_mfma_f32_16x16x32_bf16 v[96:99], v[200:203], v[216:219], v[96:99]
	v_mfma_f32_16x16x32_bf16 v[84:87], v[190:193], v[224:227], v[84:87]
	v_mfma_f32_16x16x32_bf16 v[80:83], v[200:203], v[224:227], v[80:83]
	v_mfma_f32_16x16x32_bf16 v[68:71], v[190:193], v[232:235], v[68:71]
	v_mfma_f32_16x16x32_bf16 v[64:67], v[200:203], v[232:235], v[64:67]
	v_mfma_f32_16x16x32_bf16 v[116:119], v[194:197], v[212:215], v[116:119]
	v_mfma_f32_16x16x32_bf16 v[112:115], v[204:207], v[212:215], v[112:115]
	v_mfma_f32_16x16x32_bf16 v[100:103], v[194:197], v[220:223], v[100:103]
	v_mfma_f32_16x16x32_bf16 v[96:99], v[204:207], v[220:223], v[96:99]
	v_mfma_f32_16x16x32_bf16 v[84:87], v[194:197], v[228:231], v[84:87]
	v_mfma_f32_16x16x32_bf16 v[80:83], v[204:207], v[228:231], v[80:83]
	v_mfma_f32_16x16x32_bf16 v[68:71], v[194:197], v[236:239], v[68:71]
	v_mfma_f32_16x16x32_bf16 v[64:67], v[204:207], v[236:239], v[64:67]
	s_setprio 0
	s_barrier
	s_add_i32 s39, s81, s70
	v_lshl_add_u64 v[172:173], s[28:29], 0, v[130:131]
	s_mov_b32 m0, s39
	ds_read_b128 v[208:211], v180 offset:16384
	ds_read_b128 v[212:215], v180 offset:17408
	ds_read_b128 v[216:219], v180 offset:18432
	ds_read_b128 v[220:223], v180 offset:19456
	ds_read_b128 v[224:227], v180 offset:20480
	ds_read_b128 v[228:231], v180 offset:21504
	ds_read_b128 v[232:235], v180 offset:22528
	ds_read_b128 v[236:239], v180 offset:23552
	global_load_lds_dwordx4 v[172:173], off
	s_add_i32 m0, s39, 0x2000
	s_add_u32 s40, s28, 0x40000
	v_lshl_add_u64 v[240:241], s[28:29], 0, v[134:135]
	s_addc_u32 s41, s29, 0
	s_add_i32 s39, s82, s70
	global_load_lds_dwordx4 v[240:241], off
	v_lshl_add_u64 v[242:243], s[40:41], 0, v[130:131]
	s_mov_b32 m0, s39
	v_lshl_add_u64 v[244:245], s[30:31], 0, v[132:133]
	global_load_lds_dwordx4 v[242:243], off
	v_lshl_add_u64 v[242:243], s[40:41], 0, v[134:135]
	s_add_i32 m0, s39, 0x2000
	s_nop 0
	global_load_lds_dwordx4 v[242:243], off
	v_lshl_add_u64 v[242:243], s[30:31], 0, v[128:129]
	s_mov_b32 m0, s71
	s_nop 0
	global_load_lds_dwordx4 v[242:243], off
	s_mov_b32 m0, s72
	s_nop 0
	global_load_lds_dwordx4 v[244:245], off
	s_waitcnt vmcnt(8)
	s_waitcnt lgkmcnt(0)
	s_barrier
	s_setprio 1
	s_waitcnt lgkmcnt(0)
	v_mfma_f32_16x16x32_bf16 v[60:63], v[164:167], v[208:211], v[60:63]
	v_mfma_f32_16x16x32_bf16 v[56:59], v[182:185], v[208:211], v[56:59]
	v_mfma_f32_16x16x32_bf16 v[44:47], v[164:167], v[216:219], v[44:47]
	v_mfma_f32_16x16x32_bf16 v[40:43], v[182:185], v[216:219], v[40:43]
	v_mfma_f32_16x16x32_bf16 v[28:31], v[164:167], v[224:227], v[28:31]
	v_mfma_f32_16x16x32_bf16 v[24:27], v[182:185], v[224:227], v[24:27]
	v_mfma_f32_16x16x32_bf16 v[12:15], v[164:167], v[232:235], v[12:15]
	v_mfma_f32_16x16x32_bf16 v[8:11], v[182:185], v[232:235], v[8:11]
	v_mfma_f32_16x16x32_bf16 v[60:63], v[168:171], v[212:215], v[60:63]
	v_mfma_f32_16x16x32_bf16 v[56:59], v[186:189], v[212:215], v[56:59]
	v_mfma_f32_16x16x32_bf16 v[44:47], v[168:171], v[220:223], v[44:47]
	v_mfma_f32_16x16x32_bf16 v[40:43], v[186:189], v[220:223], v[40:43]
	v_mfma_f32_16x16x32_bf16 v[28:31], v[168:171], v[228:231], v[28:31]
	v_mfma_f32_16x16x32_bf16 v[24:27], v[186:189], v[228:231], v[24:27]
	v_mfma_f32_16x16x32_bf16 v[12:15], v[168:171], v[236:239], v[12:15]
	v_mfma_f32_16x16x32_bf16 v[8:11], v[186:189], v[236:239], v[8:11]
	s_setprio 0
	s_setprio 1
	v_mfma_f32_16x16x32_bf16 v[52:55], v[190:193], v[208:211], v[52:55]
	v_mfma_f32_16x16x32_bf16 v[48:51], v[200:203], v[208:211], v[48:51]
	v_mfma_f32_16x16x32_bf16 v[36:39], v[190:193], v[216:219], v[36:39]
	v_mfma_f32_16x16x32_bf16 v[32:35], v[200:203], v[216:219], v[32:35]
	v_mfma_f32_16x16x32_bf16 v[20:23], v[190:193], v[224:227], v[20:23]
	v_mfma_f32_16x16x32_bf16 v[16:19], v[200:203], v[224:227], v[16:19]
	v_mfma_f32_16x16x32_bf16 v[4:7], v[190:193], v[232:235], v[4:7]
	v_mfma_f32_16x16x32_bf16 v[0:3], v[200:203], v[232:235], v[0:3]
	v_mfma_f32_16x16x32_bf16 v[52:55], v[194:197], v[212:215], v[52:55]
	v_mfma_f32_16x16x32_bf16 v[48:51], v[204:207], v[212:215], v[48:51]
	v_mfma_f32_16x16x32_bf16 v[36:39], v[194:197], v[220:223], v[36:39]
	v_mfma_f32_16x16x32_bf16 v[32:35], v[204:207], v[220:223], v[32:35]
	v_mfma_f32_16x16x32_bf16 v[20:23], v[194:197], v[228:231], v[20:23]
	v_mfma_f32_16x16x32_bf16 v[16:19], v[204:207], v[228:231], v[16:19]
	v_mfma_f32_16x16x32_bf16 v[4:7], v[194:197], v[236:239], v[4:7]
	v_mfma_f32_16x16x32_bf16 v[0:3], v[204:207], v[236:239], v[0:3]
	s_setprio 0
	s_barrier
.Lp1_seg3:
	s_add_i32 s39, 0, 0x18000
	s_add_i32 s40, 0, 0x1c000
	v_add_u32_e32 v186, s39, v175
	v_add_u32_e32 v199, s40, v175
	ds_read_b128 v[164:167], v186
	ds_read_b128 v[168:171], v186 offset:1024
	ds_read_b128 v[182:185], v186 offset:2048
	ds_read_b128 v[186:189], v186 offset:3072
	ds_read_b128 v[190:193], v199
	ds_read_b128 v[194:197], v199 offset:1024
	ds_read_b128 v[200:203], v199 offset:2048
	ds_read_b128 v[204:207], v199 offset:3072
	s_add_u32 s30, s30, 0x40000
	s_addc_u32 s31, s31, 0
	s_mov_b32 m0, s73
	v_lshl_add_u64 v[246:247], s[30:31], 0, v[128:129]
	ds_read_b128 v[208:211], v180 offset:32768
	ds_read_b128 v[212:215], v180 offset:33792
	ds_read_b128 v[216:219], v180 offset:34816
	ds_read_b128 v[220:223], v180 offset:35840
	ds_read_b128 v[224:227], v180 offset:36864
	ds_read_b128 v[228:231], v180 offset:37888
	ds_read_b128 v[232:235], v180 offset:38912
	ds_read_b128 v[236:239], v180 offset:39936
	global_load_lds_dwordx4 v[246:247], off
	v_lshl_add_u64 v[246:247], s[30:31], 0, v[132:133]
	s_mov_b32 m0, s74
	s_nop 0
	global_load_lds_dwordx4 v[246:247], off
	s_waitcnt vmcnt(8)
	s_waitcnt lgkmcnt(0)
	s_barrier
	s_setprio 1
	s_waitcnt lgkmcnt(0)
	v_mfma_f32_16x16x32_bf16 v[124:127], v[164:167], v[208:211], v[124:127]
	v_mfma_f32_16x16x32_bf16 v[120:123], v[182:185], v[208:211], v[120:123]
	v_mfma_f32_16x16x32_bf16 v[108:111], v[164:167], v[216:219], v[108:111]
	v_mfma_f32_16x16x32_bf16 v[104:107], v[182:185], v[216:219], v[104:107]
	v_mfma_f32_16x16x32_bf16 v[92:95], v[164:167], v[224:227], v[92:95]
	v_mfma_f32_16x16x32_bf16 v[88:91], v[182:185], v[224:227], v[88:91]
	v_mfma_f32_16x16x32_bf16 v[76:79], v[164:167], v[232:235], v[76:79]
	v_mfma_f32_16x16x32_bf16 v[72:75], v[182:185], v[232:235], v[72:75]
	v_mfma_f32_16x16x32_bf16 v[124:127], v[168:171], v[212:215], v[124:127]
	v_mfma_f32_16x16x32_bf16 v[120:123], v[186:189], v[212:215], v[120:123]
	v_mfma_f32_16x16x32_bf16 v[108:111], v[168:171], v[220:223], v[108:111]
	v_mfma_f32_16x16x32_bf16 v[104:107], v[186:189], v[220:223], v[104:107]
	v_mfma_f32_16x16x32_bf16 v[92:95], v[168:171], v[228:231], v[92:95]
	v_mfma_f32_16x16x32_bf16 v[88:91], v[186:189], v[228:231], v[88:91]
	v_mfma_f32_16x16x32_bf16 v[76:79], v[168:171], v[236:239], v[76:79]
	v_mfma_f32_16x16x32_bf16 v[72:75], v[186:189], v[236:239], v[72:75]
	s_setprio 0
	s_setprio 1
	v_mfma_f32_16x16x32_bf16 v[116:119], v[190:193], v[208:211], v[116:119]
	v_mfma_f32_16x16x32_bf16 v[112:115], v[200:203], v[208:211], v[112:115]
	v_mfma_f32_16x16x32_bf16 v[100:103], v[190:193], v[216:219], v[100:103]
	v_mfma_f32_16x16x32_bf16 v[96:99], v[200:203], v[216:219], v[96:99]
	v_mfma_f32_16x16x32_bf16 v[84:87], v[190:193], v[224:227], v[84:87]
	v_mfma_f32_16x16x32_bf16 v[80:83], v[200:203], v[224:227], v[80:83]
	v_mfma_f32_16x16x32_bf16 v[68:71], v[190:193], v[232:235], v[68:71]
	v_mfma_f32_16x16x32_bf16 v[64:67], v[200:203], v[232:235], v[64:67]
	v_mfma_f32_16x16x32_bf16 v[116:119], v[194:197], v[212:215], v[116:119]
	v_mfma_f32_16x16x32_bf16 v[112:115], v[204:207], v[212:215], v[112:115]
	v_mfma_f32_16x16x32_bf16 v[100:103], v[194:197], v[220:223], v[100:103]
	v_mfma_f32_16x16x32_bf16 v[96:99], v[204:207], v[220:223], v[96:99]
	v_mfma_f32_16x16x32_bf16 v[84:87], v[194:197], v[228:231], v[84:87]
	v_mfma_f32_16x16x32_bf16 v[80:83], v[204:207], v[228:231], v[80:83]
	v_mfma_f32_16x16x32_bf16 v[68:71], v[194:197], v[236:239], v[68:71]
	v_mfma_f32_16x16x32_bf16 v[64:67], v[204:207], v[236:239], v[64:67]
	s_setprio 0
	s_barrier
	s_add_i32 s30, s39, s70
	v_lshl_add_u64 v[172:173], v[172:173], 0, s[8:9]
	s_mov_b32 m0, s30
	ds_read_b128 v[208:211], v180 offset:49152
	ds_read_b128 v[212:215], v180 offset:50176
	ds_read_b128 v[216:219], v180 offset:51200
	ds_read_b128 v[220:223], v180 offset:52224
	ds_read_b128 v[224:227], v180 offset:53248
	ds_read_b128 v[228:231], v180 offset:54272
	ds_read_b128 v[232:235], v180 offset:55296
	ds_read_b128 v[236:239], v180 offset:56320
	global_load_lds_dwordx4 v[172:173], off
	s_add_i32 m0, s30, 0x2000
	s_add_u32 s28, s28, 0x40080
	v_lshl_add_u64 v[172:173], v[240:241], 0, s[8:9]
	s_addc_u32 s29, s29, 0
	s_add_i32 s30, s40, s70
	global_load_lds_dwordx4 v[172:173], off
	v_lshl_add_u64 v[172:173], s[28:29], 0, v[130:131]
	s_mov_b32 m0, s30
	s_nop 0
	global_load_lds_dwordx4 v[172:173], off
	v_lshl_add_u64 v[172:173], s[28:29], 0, v[134:135]
	s_add_i32 m0, s30, 0x2000
	s_nop 0
	global_load_lds_dwordx4 v[172:173], off
	v_lshl_add_u64 v[172:173], v[242:243], 0, s[8:9]
	s_mov_b32 m0, s76
	s_nop 0
	global_load_lds_dwordx4 v[172:173], off
	v_lshl_add_u64 v[172:173], v[244:245], 0, s[8:9]
	s_mov_b32 m0, s77
	s_nop 0
	global_load_lds_dwordx4 v[172:173], off
	s_waitcnt vmcnt(8)
	s_waitcnt lgkmcnt(0)
	s_barrier
	s_setprio 1
	s_waitcnt lgkmcnt(0)
	v_mfma_f32_16x16x32_bf16 v[60:63], v[164:167], v[208:211], v[60:63]
	v_mfma_f32_16x16x32_bf16 v[56:59], v[182:185], v[208:211], v[56:59]
	v_mfma_f32_16x16x32_bf16 v[44:47], v[164:167], v[216:219], v[44:47]
	v_mfma_f32_16x16x32_bf16 v[40:43], v[182:185], v[216:219], v[40:43]
	v_mfma_f32_16x16x32_bf16 v[28:31], v[164:167], v[224:227], v[28:31]
	v_mfma_f32_16x16x32_bf16 v[24:27], v[182:185], v[224:227], v[24:27]
	v_mfma_f32_16x16x32_bf16 v[12:15], v[164:167], v[232:235], v[12:15]
	v_mfma_f32_16x16x32_bf16 v[8:11], v[182:185], v[232:235], v[8:11]
	v_mfma_f32_16x16x32_bf16 v[60:63], v[168:171], v[212:215], v[60:63]
	v_mfma_f32_16x16x32_bf16 v[56:59], v[186:189], v[212:215], v[56:59]
	v_mfma_f32_16x16x32_bf16 v[44:47], v[168:171], v[220:223], v[44:47]
	v_mfma_f32_16x16x32_bf16 v[40:43], v[186:189], v[220:223], v[40:43]
	v_mfma_f32_16x16x32_bf16 v[28:31], v[168:171], v[228:231], v[28:31]
	v_mfma_f32_16x16x32_bf16 v[24:27], v[186:189], v[228:231], v[24:27]
	v_mfma_f32_16x16x32_bf16 v[12:15], v[168:171], v[236:239], v[12:15]
	v_mfma_f32_16x16x32_bf16 v[8:11], v[186:189], v[236:239], v[8:11]
	s_setprio 0
	s_setprio 1
	v_mfma_f32_16x16x32_bf16 v[52:55], v[190:193], v[208:211], v[52:55]
	v_mfma_f32_16x16x32_bf16 v[48:51], v[200:203], v[208:211], v[48:51]
	v_mfma_f32_16x16x32_bf16 v[36:39], v[190:193], v[216:219], v[36:39]
	v_mfma_f32_16x16x32_bf16 v[32:35], v[200:203], v[216:219], v[32:35]
	v_mfma_f32_16x16x32_bf16 v[20:23], v[190:193], v[224:227], v[20:23]
	v_mfma_f32_16x16x32_bf16 v[16:19], v[200:203], v[224:227], v[16:19]
	v_mfma_f32_16x16x32_bf16 v[4:7], v[190:193], v[232:235], v[4:7]
	v_mfma_f32_16x16x32_bf16 v[0:3], v[200:203], v[232:235], v[0:3]
	v_mfma_f32_16x16x32_bf16 v[52:55], v[194:197], v[212:215], v[52:55]
	v_mfma_f32_16x16x32_bf16 v[48:51], v[204:207], v[212:215], v[48:51]
	v_mfma_f32_16x16x32_bf16 v[36:39], v[194:197], v[220:223], v[36:39]
	v_mfma_f32_16x16x32_bf16 v[32:35], v[204:207], v[220:223], v[32:35]
	v_mfma_f32_16x16x32_bf16 v[20:23], v[194:197], v[228:231], v[20:23]
	v_mfma_f32_16x16x32_bf16 v[16:19], v[204:207], v[228:231], v[16:19]
	v_mfma_f32_16x16x32_bf16 v[4:7], v[194:197], v[236:239], v[4:7]
	v_mfma_f32_16x16x32_bf16 v[0:3], v[204:207], v[236:239], v[0:3]
	s_setprio 0
	s_barrier
	s_add_i32 s38, s38, 2
	s_add_u32 s26, s26, 0x100
	s_addc_u32 s27, s27, 0
	s_add_u32 s36, s36, 0x100
	s_addc_u32 s37, s37, 0
	s_cmp_gt_u32 s38, 13
	s_cbranch_scc0 .LBB0_157
	s_and_b64 vcc, exec, s[10:11]
	s_cbranch_vccz .LBB0_160
	s_barrier
